# P6 SwiGLU epilogue: 8 serialized rowsq loads (each with vmcnt(0)) hoisted into one batch with a single wait; on top of v29
# speedup vs baseline: 1.0096x; 1.0096x over previous
; __device__ __forceinline__ unsigned cvt_pk_bf16(float lo, float hi) { unsigned r; asm volatile("v_cvt_pk_bf16_f32 %0, %1, %2" : "=v"(r) : "v"(lo), "v"(hi)); return r; }
; __device__ __forceinline__ float exp2_fast(float x) { return __builtin_amdgcn_exp2f(x); }
; __device__ __forceinline__ float rstd_of(float sq, float inv_n) { return 1.0f / sqrtf(sq * inv_n + EPSN); }
;     __device__ __forceinline__ void operator()(const f32x4 (&acc)[2][2][4][2], const Unit& u, int wr, int wc, int fr, int fq) const {
;         const int row0 = u.pm * BM + wr * 64 + fr, col0 = u.pn * 128 + wc * 32 + 8 * fq;
; #pragma unroll
;         for (int ai = 0; ai < 2; ++ai)
; #pragma unroll
;             for (int m = 0; m < 4; ++m) {
;                 const int row = row0 + ai * HALF + m * 16;
;                 const float rs = PRENORM ? 1.0f : rstd_of(rowsq[row], 1.f / 2048.f);
;                 float hv[8];
; #pragma unroll
;                 for (int n = 0; n < 2; ++n)
; #pragma unroll
;                     for (int e = 0; e < 4; ++e) { const float g = acc[ai][0][m][n][e] * rs, uu = acc[ai][1][m][n][e] * rs;
;                         hv[n * 4 + e] = g * uu * __builtin_amdgcn_rcpf(1.0f + exp2_fast(-g * LOG2E)); }
;                 u32x4 w; w.x = cvt_pk_bf16(hv[0], hv[1]); w.y = cvt_pk_bf16(hv[2], hv[3]); w.z = cvt_pk_bf16(hv[4], hv[5]); w.w = cvt_pk_bf16(hv[6], hv[7]);
;                 *(u32x4*)(H + (size_t)row * DFF + col0) = w;
.LBB0_1282:
	v_lshl_add_u32 v136, s8, 8, v143
	v_ashrrev_i32_e32 v137, 31, v136
	v_lshl_add_u64 v[160:161], v[136:137], 2, s[12:13]
	global_load_dword v137, v[160:161], off
	global_load_dword v186, v[160:161], off offset:64
	global_load_dword v187, v[160:161], off offset:128
	global_load_dword v188, v[160:161], off offset:192
	global_load_dword v189, v[160:161], off offset:512
	global_load_dword v190, v[160:161], off offset:576
	global_load_dword v191, v[160:161], off offset:640
	global_load_dword v192, v[160:161], off offset:704
	v_mov_b32_e32 v168, v124
	v_mov_b32_e32 v124, v126
	v_mov_b32_e32 v126, v120
	v_mov_b32_e32 v169, v116
	v_mov_b32_e32 v116, v125
	v_mov_b32_e32 v125, v118
	v_mov_b32_e32 v118, v127
	v_mov_b32_e32 v127, v112
	v_mov_b32_e32 v112, v121
	v_lshl_or_b32 v166, s9, 7, v147
	v_mov_b32_e32 v170, v122
	v_mov_b32_e32 v171, v114
	v_mov_b32_e32 v114, v123
	v_mov_b64_e32 v[122:123], s[10:11]
	v_ashrrev_i32_e32 v167, 31, v166
	v_mad_i64_i32 v[172:173], s[8:9], v136, s49, v[122:123]
	v_or_b32_e32 v174, 16, v136
	v_ashrrev_i32_e32 v175, 31, v174
	s_waitcnt vmcnt(0)
	v_fmamk_f32 v120, v137, 0x3a000000, v163
	v_mul_f32_e32 v121, 0x4f800000, v120
	v_cmp_gt_f32_e32 vcc, s48, v120
	s_nop 1
	v_cndmask_b32_e32 v137, v120, v121, vcc
	v_sqrt_f32_e32 v165, v137
	v_lshlrev_b64 v[120:121], 1, v[166:167]
	v_lshl_add_u64 v[166:167], v[172:173], 0, v[120:121]
	v_add_u32_e32 v172, -1, v165
	v_add_u32_e32 v173, 1, v165
	v_fma_f32 v176, -v172, v165, v137
	v_fma_f32 v177, -v173, v165, v137
	v_cmp_ge_f32_e64 s[8:9], 0, v176
	s_nop 1
	v_cndmask_b32_e64 v165, v165, v172, s[8:9]
	v_cmp_lt_f32_e64 s[8:9], 0, v177
	s_nop 1
	v_cndmask_b32_e64 v165, v165, v173, s[8:9]
	v_mul_f32_e32 v172, 0x37800000, v165
	v_cndmask_b32_e32 v165, v165, v172, vcc
	v_cmp_class_f32_e32 vcc, v137, v164
	v_lshl_add_u64 v[172:173], v[174:175], 2, s[12:13]
	s_nop 0
	v_cndmask_b32_e32 v137, v165, v137, vcc
	v_div_scale_f32 v165, s[8:9], v137, v137, 1.0
	v_rcp_f32_e32 v176, v165
	v_div_scale_f32 v175, vcc, 1.0, v137, 1.0
	v_fma_f32 v177, -v165, v176, 1.0
	v_fmac_f32_e32 v176, v177, v176
	v_mul_f32_e32 v177, v175, v176
	v_fma_f32 v185, -v165, v177, v175
	v_fmac_f32_e32 v177, v185, v176
	v_fma_f32 v165, -v165, v177, v175
	v_div_fmas_f32 v165, v165, v176, v177
	v_div_fixup_f32 v176, v165, v137, 1.0
	v_pk_mul_f32 v[114:115], v[114:115], v[176:177] op_sel_hi:[1,0]
	v_pk_mul_f32 v[168:169], v[168:169], v[176:177] op_sel_hi:[1,0]
	v_pk_mul_f32 v[116:117], v[116:117], v[176:177] op_sel_hi:[1,0]
	v_pk_mul_f32 v[124:125], v[124:125], v[176:177] op_sel_hi:[1,0]
	v_pk_mul_f32 v[118:119], v[118:119], v[176:177] op_sel_hi:[1,0]
	v_pk_mul_f32 v[126:127], v[126:127], v[176:177] op_sel_hi:[1,0]
	v_pk_mul_f32 v[112:113], v[112:113], v[176:177] op_sel_hi:[1,0]
	v_pk_mul_f32 v[170:171], v[170:171], v[176:177] op_sel_hi:[1,0]
	v_mul_f32_e32 v115, v114, v115
	v_mul_f32_e32 v114, 0xbfb8aa3b, v114
	v_mul_f32_e32 v137, v168, v169
	v_mul_f32_e32 v165, 0xbfb8aa3b, v168
	v_mul_f32_e32 v117, v116, v117
	v_mul_f32_e32 v116, 0xbfb8aa3b, v116
	v_mul_f32_e32 v125, v124, v125
	v_mul_f32_e32 v124, 0xbfb8aa3b, v124
	v_mul_f32_e32 v119, v118, v119
	v_mul_f32_e32 v118, 0xbfb8aa3b, v118
	v_mul_f32_e32 v127, v126, v127
	v_mul_f32_e32 v126, 0xbfb8aa3b, v126
	v_mul_f32_e32 v113, v112, v113
	v_mul_f32_e32 v112, 0xbfb8aa3b, v112
	v_mul_f32_e32 v169, 0xbfb8aa3b, v170
	v_exp_f32_e32 v114, v114
	v_exp_f32_e32 v165, v165
	v_exp_f32_e32 v116, v116
	v_exp_f32_e32 v124, v124
	v_exp_f32_e32 v118, v118
	v_exp_f32_e32 v126, v126
	v_exp_f32_e32 v112, v112
	v_exp_f32_e32 v169, v169
	v_add_f32_e32 v114, 1.0, v114
	v_add_f32_e32 v165, 1.0, v165
	v_add_f32_e32 v116, 1.0, v116
	v_add_f32_e32 v124, 1.0, v124
	v_add_f32_e32 v118, 1.0, v118
	v_add_f32_e32 v126, 1.0, v126
	v_add_f32_e32 v112, 1.0, v112
	v_add_f32_e32 v169, 1.0, v169
	v_rcp_f32_e32 v114, v114
	v_rcp_f32_e32 v165, v165
	v_rcp_f32_e32 v116, v116
	v_rcp_f32_e32 v124, v124
	v_rcp_f32_e32 v118, v118
	v_rcp_f32_e32 v126, v126
	v_rcp_f32_e32 v112, v112
	v_rcp_f32_e32 v169, v169
	v_mul_f32_e32 v168, v170, v171
	v_mul_f32_e32 v115, v115, v114
	v_mul_f32_e32 v137, v137, v165
	v_mul_f32_e32 v116, v117, v116
	v_mul_f32_e32 v117, v125, v124
	v_mul_f32_e32 v118, v119, v118
	v_mul_f32_e32 v119, v127, v126
	v_mul_f32_e32 v124, v113, v112
	v_mul_f32_e32 v125, v168, v169
	v_cvt_pk_bf16_f32 v112, v137, v116
	v_cvt_pk_bf16_f32 v113, v117, v118
	v_cvt_pk_bf16_f32 v114, v119, v124
	v_cvt_pk_bf16_f32 v115, v125, v115
	global_store_dwordx4 v[166:167], v[112:115], off
	s_nop 1
	v_mov_b32_e32 v114, v186
	s_nop 0
	v_mov_b32_e32 v113, v100
	v_mov_b32_e32 v100, v109
	v_mov_b32_e32 v109, v102
	v_mov_b32_e32 v102, v111
	v_mov_b32_e32 v111, v96
	v_mov_b32_e32 v96, v105
	v_mov_b32_e32 v105, v98
	v_mov_b32_e32 v98, v107
	v_mov_b32_e32 v112, v108
	v_mov_b32_e32 v108, v110
	v_mov_b32_e32 v110, v104
	v_mov_b32_e32 v104, v106
	v_or_b32_e32 v106, 32, v136
	s_nop 0
	v_fmamk_f32 v107, v114, 0x3a000000, v163
	v_mul_f32_e32 v114, 0x4f800000, v107
	v_cmp_gt_f32_e32 vcc, s48, v107
	s_nop 1
	v_cndmask_b32_e32 v116, v107, v114, vcc
	v_sqrt_f32_e32 v117, v116
	v_mad_i64_i32 v[114:115], s[8:9], v174, s49, v[122:123]
	v_ashrrev_i32_e32 v107, 31, v106
	v_add_u32_e32 v118, -1, v117
	v_add_u32_e32 v119, 1, v117
	v_fma_f32 v124, -v118, v117, v116
	v_fma_f32 v125, -v119, v117, v116
	v_cmp_ge_f32_e64 s[8:9], 0, v124
	v_lshl_add_u64 v[114:115], v[114:115], 0, v[120:121]
	s_nop 0
	v_cndmask_b32_e64 v117, v117, v118, s[8:9]
	v_cmp_lt_f32_e64 s[8:9], 0, v125
	s_nop 1
	v_cndmask_b32_e64 v117, v117, v119, s[8:9]
	v_mul_f32_e32 v118, 0x37800000, v117
	v_cndmask_b32_e32 v117, v117, v118, vcc
	v_cmp_class_f32_e32 vcc, v116, v164
	s_nop 1
; __device__ __forceinline__ unsigned cvt_pk_bf16(float lo, float hi) { unsigned r; asm volatile("v_cvt_pk_bf16_f32 %0, %1, %2" : "=v"(r) : "v"(lo), "v"(hi)); return r; }
; __device__ __forceinline__ float exp2_fast(float x) { return __builtin_amdgcn_exp2f(x); }
; __device__ __forceinline__ float rstd_of(float sq, float inv_n) { return 1.0f / sqrtf(sq * inv_n + EPSN); }
;     __device__ __forceinline__ void operator()(const f32x4 (&acc)[2][2][4][2], const Unit& u, int wr, int wc, int fr, int fq) const {
;     ...
;             for (int m = 0; m < 4; ++m) {
;                 const int row = row0 + ai * HALF + m * 16;
;                 const float rs = PRENORM ? 1.0f : rstd_of(rowsq[row], 1.f / 2048.f);
;                 float hv[8];
; #pragma unroll
;                 for (int n = 0; n < 2; ++n)
; #pragma unroll
;                     for (int e = 0; e < 4; ++e) { const float g = acc[ai][0][m][n][e] * rs, uu = acc[ai][1][m][n][e] * rs;
;                         hv[n * 4 + e] = g * uu * __builtin_amdgcn_rcpf(1.0f + exp2_fast(-g * LOG2E)); }
;                 u32x4 w; w.x = cvt_pk_bf16(hv[0], hv[1]); w.y = cvt_pk_bf16(hv[2], hv[3]); w.z = cvt_pk_bf16(hv[4], hv[5]); w.w = cvt_pk_bf16(hv[6], hv[7]);
;                 *(u32x4*)(H + (size_t)row * DFF + col0) = w;
	v_cndmask_b32_e32 v118, v117, v116, vcc
	v_div_scale_f32 v119, s[8:9], v118, v118, 1.0
	v_rcp_f32_e32 v124, v119
	v_lshl_add_u64 v[116:117], v[106:107], 2, s[12:13]
	v_div_scale_f32 v107, vcc, 1.0, v118, 1.0
	v_fma_f32 v125, -v119, v124, 1.0
	v_fmac_f32_e32 v124, v125, v124
	v_mul_f32_e32 v125, v107, v124
	v_fma_f32 v126, -v119, v125, v107
	v_fmac_f32_e32 v125, v126, v124
	v_fma_f32 v107, -v119, v125, v107
	v_div_fmas_f32 v107, v107, v124, v125
	v_div_fixup_f32 v118, v107, v118, 1.0
	v_pk_mul_f32 v[98:99], v[98:99], v[118:119] op_sel_hi:[1,0]
	v_pk_mul_f32 v[112:113], v[112:113], v[118:119] op_sel_hi:[1,0]
	v_pk_mul_f32 v[100:101], v[100:101], v[118:119] op_sel_hi:[1,0]
	v_pk_mul_f32 v[108:109], v[108:109], v[118:119] op_sel_hi:[1,0]
	v_pk_mul_f32 v[102:103], v[102:103], v[118:119] op_sel_hi:[1,0]
	v_pk_mul_f32 v[110:111], v[110:111], v[118:119] op_sel_hi:[1,0]
	v_pk_mul_f32 v[96:97], v[96:97], v[118:119] op_sel_hi:[1,0]
	v_pk_mul_f32 v[104:105], v[104:105], v[118:119] op_sel_hi:[1,0]
	v_mul_f32_e32 v99, v98, v99
	v_mul_f32_e32 v98, 0xbfb8aa3b, v98
	v_mul_f32_e32 v107, v112, v113
	v_mul_f32_e32 v112, 0xbfb8aa3b, v112
	v_mul_f32_e32 v101, v100, v101
	v_mul_f32_e32 v100, 0xbfb8aa3b, v100
	v_mul_f32_e32 v109, v108, v109
	v_mul_f32_e32 v108, 0xbfb8aa3b, v108
	v_mul_f32_e32 v103, v102, v103
	v_mul_f32_e32 v102, 0xbfb8aa3b, v102
	v_mul_f32_e32 v111, v110, v111
	v_mul_f32_e32 v110, 0xbfb8aa3b, v110
	v_mul_f32_e32 v97, v96, v97
	v_mul_f32_e32 v96, 0xbfb8aa3b, v96
	v_mul_f32_e32 v105, v104, v105
	v_mul_f32_e32 v104, 0xbfb8aa3b, v104
	v_exp_f32_e32 v98, v98
	v_exp_f32_e32 v112, v112
	v_exp_f32_e32 v100, v100
	v_exp_f32_e32 v108, v108
	v_exp_f32_e32 v102, v102
	v_exp_f32_e32 v110, v110
	v_exp_f32_e32 v96, v96
	v_exp_f32_e32 v104, v104
	v_add_f32_e32 v98, 1.0, v98
	v_add_f32_e32 v112, 1.0, v112
	v_add_f32_e32 v100, 1.0, v100
	v_add_f32_e32 v108, 1.0, v108
	v_add_f32_e32 v102, 1.0, v102
	v_add_f32_e32 v110, 1.0, v110
	v_add_f32_e32 v96, 1.0, v96
	v_add_f32_e32 v104, 1.0, v104
	v_rcp_f32_e32 v98, v98
	v_rcp_f32_e32 v112, v112
	v_rcp_f32_e32 v100, v100
	v_rcp_f32_e32 v108, v108
	v_rcp_f32_e32 v102, v102
	v_rcp_f32_e32 v110, v110
	v_rcp_f32_e32 v96, v96
	v_rcp_f32_e32 v104, v104
	v_mul_f32_e32 v99, v99, v98
	v_mul_f32_e32 v107, v107, v112
	v_mul_f32_e32 v100, v101, v100
	v_mul_f32_e32 v101, v109, v108
	v_mul_f32_e32 v102, v103, v102
	v_mul_f32_e32 v103, v111, v110
	v_mul_f32_e32 v108, v97, v96
	v_mul_f32_e32 v104, v105, v104
	v_cvt_pk_bf16_f32 v96, v107, v100
	v_cvt_pk_bf16_f32 v97, v101, v102
	v_cvt_pk_bf16_f32 v98, v103, v108
	v_cvt_pk_bf16_f32 v99, v104, v99
	global_store_dwordx4 v[114:115], v[96:99], off
	s_nop 1
	v_mov_b32_e32 v98, v187
	s_nop 0
	v_mov_b32_e32 v97, v84
	v_mov_b32_e32 v84, v93
	v_mov_b32_e32 v93, v86
	v_mov_b32_e32 v86, v95
	v_mov_b32_e32 v95, v80
	v_mov_b32_e32 v80, v89
	v_mov_b32_e32 v89, v82
	v_mov_b32_e32 v82, v91
	v_mov_b32_e32 v96, v92
	v_mov_b32_e32 v92, v94
	v_mov_b32_e32 v94, v88
	v_mov_b32_e32 v88, v90
	v_or_b32_e32 v90, 48, v136
	s_nop 0
	v_fmamk_f32 v91, v98, 0x3a000000, v163
	v_mul_f32_e32 v98, 0x4f800000, v91
	v_cmp_gt_f32_e32 vcc, s48, v91
	s_nop 1
	v_cndmask_b32_e32 v100, v91, v98, vcc
	v_sqrt_f32_e32 v101, v100
	v_mad_i64_i32 v[98:99], s[8:9], v106, s49, v[122:123]
	v_ashrrev_i32_e32 v91, 31, v90
	v_add_u32_e32 v102, -1, v101
	v_add_u32_e32 v103, 1, v101
	v_fma_f32 v104, -v102, v101, v100
	v_fma_f32 v105, -v103, v101, v100
	v_cmp_ge_f32_e64 s[8:9], 0, v104
	v_lshl_add_u64 v[98:99], v[98:99], 0, v[120:121]
	s_nop 0
	v_cndmask_b32_e64 v101, v101, v102, s[8:9]
	v_cmp_lt_f32_e64 s[8:9], 0, v105
	s_nop 1
	v_cndmask_b32_e64 v101, v101, v103, s[8:9]
	v_mul_f32_e32 v102, 0x37800000, v101
	v_cndmask_b32_e32 v101, v101, v102, vcc
	v_cmp_class_f32_e32 vcc, v100, v164
	s_nop 1
	v_cndmask_b32_e32 v102, v101, v100, vcc
	v_div_scale_f32 v103, s[8:9], v102, v102, 1.0
	v_rcp_f32_e32 v104, v103
	v_lshl_add_u64 v[100:101], v[90:91], 2, s[12:13]
	v_div_scale_f32 v91, vcc, 1.0, v102, 1.0
	v_fma_f32 v105, -v103, v104, 1.0
	v_fmac_f32_e32 v104, v105, v104
	v_mul_f32_e32 v105, v91, v104
	v_fma_f32 v106, -v103, v105, v91
	v_fmac_f32_e32 v105, v106, v104
	v_fma_f32 v91, -v103, v105, v91
	v_div_fmas_f32 v91, v91, v104, v105
	v_div_fixup_f32 v102, v91, v102, 1.0
	v_pk_mul_f32 v[82:83], v[82:83], v[102:103] op_sel_hi:[1,0]
	v_pk_mul_f32 v[96:97], v[96:97], v[102:103] op_sel_hi:[1,0]
	v_pk_mul_f32 v[84:85], v[84:85], v[102:103] op_sel_hi:[1,0]
	v_pk_mul_f32 v[92:93], v[92:93], v[102:103] op_sel_hi:[1,0]
	v_pk_mul_f32 v[86:87], v[86:87], v[102:103] op_sel_hi:[1,0]
	v_pk_mul_f32 v[94:95], v[94:95], v[102:103] op_sel_hi:[1,0]
	v_pk_mul_f32 v[80:81], v[80:81], v[102:103] op_sel_hi:[1,0]
	v_pk_mul_f32 v[88:89], v[88:89], v[102:103] op_sel_hi:[1,0]
	v_mul_f32_e32 v83, v82, v83
	v_mul_f32_e32 v82, 0xbfb8aa3b, v82
	v_mul_f32_e32 v91, v96, v97
	v_mul_f32_e32 v96, 0xbfb8aa3b, v96
	v_mul_f32_e32 v85, v84, v85
	v_mul_f32_e32 v84, 0xbfb8aa3b, v84
	v_mul_f32_e32 v93, v92, v93
	v_mul_f32_e32 v92, 0xbfb8aa3b, v92
	v_mul_f32_e32 v87, v86, v87
	v_mul_f32_e32 v86, 0xbfb8aa3b, v86
	v_mul_f32_e32 v95, v94, v95
	v_mul_f32_e32 v94, 0xbfb8aa3b, v94
	v_mul_f32_e32 v81, v80, v81
	v_mul_f32_e32 v80, 0xbfb8aa3b, v80
	v_mul_f32_e32 v89, v88, v89
	v_mul_f32_e32 v88, 0xbfb8aa3b, v88
	v_exp_f32_e32 v82, v82
	v_exp_f32_e32 v96, v96
	v_exp_f32_e32 v84, v84
	v_exp_f32_e32 v92, v92
	v_exp_f32_e32 v86, v86
	v_exp_f32_e32 v94, v94
	v_exp_f32_e32 v80, v80
	v_exp_f32_e32 v88, v88
	v_add_f32_e32 v82, 1.0, v82
	v_add_f32_e32 v96, 1.0, v96
	v_add_f32_e32 v84, 1.0, v84
	v_add_f32_e32 v92, 1.0, v92
	v_add_f32_e32 v86, 1.0, v86
	v_add_f32_e32 v94, 1.0, v94
	v_add_f32_e32 v80, 1.0, v80
; __device__ __forceinline__ unsigned cvt_pk_bf16(float lo, float hi) { unsigned r; asm volatile("v_cvt_pk_bf16_f32 %0, %1, %2" : "=v"(r) : "v"(lo), "v"(hi)); return r; }
; __device__ __forceinline__ float exp2_fast(float x) { return __builtin_amdgcn_exp2f(x); }
; __device__ __forceinline__ float rstd_of(float sq, float inv_n) { return 1.0f / sqrtf(sq * inv_n + EPSN); }
;     __device__ __forceinline__ void operator()(const f32x4 (&acc)[2][2][4][2], const Unit& u, int wr, int wc, int fr, int fq) const {
;     ...
;             for (int m = 0; m < 4; ++m) {
;                 const int row = row0 + ai * HALF + m * 16;
;                 const float rs = PRENORM ? 1.0f : rstd_of(rowsq[row], 1.f / 2048.f);
;                 float hv[8];
; #pragma unroll
;                 for (int n = 0; n < 2; ++n)
; #pragma unroll
;                     for (int e = 0; e < 4; ++e) { const float g = acc[ai][0][m][n][e] * rs, uu = acc[ai][1][m][n][e] * rs;
;                         hv[n * 4 + e] = g * uu * __builtin_amdgcn_rcpf(1.0f + exp2_fast(-g * LOG2E)); }
;                 u32x4 w; w.x = cvt_pk_bf16(hv[0], hv[1]); w.y = cvt_pk_bf16(hv[2], hv[3]); w.z = cvt_pk_bf16(hv[4], hv[5]); w.w = cvt_pk_bf16(hv[6], hv[7]);
;                 *(u32x4*)(H + (size_t)row * DFF + col0) = w;
	v_add_f32_e32 v88, 1.0, v88
	v_rcp_f32_e32 v82, v82
	v_rcp_f32_e32 v96, v96
	v_rcp_f32_e32 v84, v84
	v_rcp_f32_e32 v92, v92
	v_rcp_f32_e32 v86, v86
	v_rcp_f32_e32 v94, v94
	v_rcp_f32_e32 v80, v80
	v_rcp_f32_e32 v88, v88
	v_mul_f32_e32 v83, v83, v82
	v_mul_f32_e32 v91, v91, v96
	v_mul_f32_e32 v84, v85, v84
	v_mul_f32_e32 v85, v93, v92
	v_mul_f32_e32 v86, v87, v86
	v_mul_f32_e32 v87, v95, v94
	v_mul_f32_e32 v92, v81, v80
	v_mul_f32_e32 v88, v89, v88
	v_cvt_pk_bf16_f32 v80, v91, v84
	v_cvt_pk_bf16_f32 v81, v85, v86
	v_cvt_pk_bf16_f32 v82, v87, v92
	v_cvt_pk_bf16_f32 v83, v88, v83
	global_store_dwordx4 v[98:99], v[80:83], off
	s_nop 1
	v_mov_b32_e32 v82, v188
	s_nop 0
	v_mov_b32_e32 v81, v68
	v_mov_b32_e32 v68, v77
	v_mov_b32_e32 v77, v70
	v_mov_b32_e32 v70, v79
	v_mov_b32_e32 v79, v64
	v_mov_b32_e32 v64, v73
	v_mov_b32_e32 v73, v66
	v_mov_b32_e32 v80, v76
	v_mov_b32_e32 v76, v78
	v_mov_b32_e32 v78, v72
	v_mov_b32_e32 v72, v74
	s_nop 0
	v_fmamk_f32 v66, v82, 0x3a000000, v163
	v_mul_f32_e32 v74, 0x4f800000, v66
	v_cmp_gt_f32_e32 vcc, s48, v66
	s_nop 1
	v_cndmask_b32_e32 v82, v66, v74, vcc
	v_sqrt_f32_e32 v83, v82
	v_mov_b32_e32 v66, v75
	v_mad_i64_i32 v[74:75], s[8:9], v90, s49, v[122:123]
	v_add_u32_e32 v84, -1, v83
	v_add_u32_e32 v85, 1, v83
	v_fma_f32 v86, -v84, v83, v82
	v_fma_f32 v87, -v85, v83, v82
	v_cmp_ge_f32_e64 s[8:9], 0, v86
	v_lshl_add_u64 v[74:75], v[74:75], 0, v[120:121]
	s_nop 0
	v_cndmask_b32_e64 v83, v83, v84, s[8:9]
	v_cmp_lt_f32_e64 s[8:9], 0, v87
	s_nop 1
	v_cndmask_b32_e64 v83, v83, v85, s[8:9]
	v_mul_f32_e32 v84, 0x37800000, v83
	v_cndmask_b32_e32 v83, v83, v84, vcc
	v_cmp_class_f32_e32 vcc, v82, v164
	s_nop 1
	v_cndmask_b32_e32 v82, v83, v82, vcc
	v_div_scale_f32 v83, s[8:9], v82, v82, 1.0
	v_rcp_f32_e32 v84, v83
	v_div_scale_f32 v85, vcc, 1.0, v82, 1.0
	v_fma_f32 v86, -v83, v84, 1.0
	v_fmac_f32_e32 v84, v86, v84
	v_mul_f32_e32 v86, v85, v84
	v_fma_f32 v87, -v83, v86, v85
	v_fmac_f32_e32 v86, v87, v84
	v_fma_f32 v83, -v83, v86, v85
	v_div_fmas_f32 v83, v83, v84, v86
	v_div_fixup_f32 v82, v83, v82, 1.0
	v_pk_mul_f32 v[66:67], v[66:67], v[82:83] op_sel_hi:[1,0]
	v_pk_mul_f32 v[80:81], v[80:81], v[82:83] op_sel_hi:[1,0]
	v_pk_mul_f32 v[68:69], v[68:69], v[82:83] op_sel_hi:[1,0]
	v_pk_mul_f32 v[76:77], v[76:77], v[82:83] op_sel_hi:[1,0]
	v_pk_mul_f32 v[70:71], v[70:71], v[82:83] op_sel_hi:[1,0]
	v_pk_mul_f32 v[78:79], v[78:79], v[82:83] op_sel_hi:[1,0]
	v_pk_mul_f32 v[64:65], v[64:65], v[82:83] op_sel_hi:[1,0]
	v_pk_mul_f32 v[72:73], v[72:73], v[82:83] op_sel_hi:[1,0]
	v_mul_f32_e32 v67, v66, v67
	v_mul_f32_e32 v66, 0xbfb8aa3b, v66
	v_mul_f32_e32 v81, v80, v81
	v_mul_f32_e32 v80, 0xbfb8aa3b, v80
	v_mul_f32_e32 v69, v68, v69
	v_mul_f32_e32 v68, 0xbfb8aa3b, v68
	v_mul_f32_e32 v77, v76, v77
	v_mul_f32_e32 v76, 0xbfb8aa3b, v76
	v_mul_f32_e32 v71, v70, v71
	v_mul_f32_e32 v70, 0xbfb8aa3b, v70
	v_mul_f32_e32 v79, v78, v79
	v_mul_f32_e32 v78, 0xbfb8aa3b, v78
	v_mul_f32_e32 v65, v64, v65
	v_mul_f32_e32 v64, 0xbfb8aa3b, v64
	v_mul_f32_e32 v73, v72, v73
	v_mul_f32_e32 v72, 0xbfb8aa3b, v72
	v_exp_f32_e32 v66, v66
	v_exp_f32_e32 v80, v80
	v_exp_f32_e32 v68, v68
	v_exp_f32_e32 v76, v76
	v_exp_f32_e32 v70, v70
	v_exp_f32_e32 v78, v78
	v_exp_f32_e32 v64, v64
	v_exp_f32_e32 v72, v72
	v_add_f32_e32 v66, 1.0, v66
	v_add_f32_e32 v80, 1.0, v80
	v_add_f32_e32 v68, 1.0, v68
	v_add_f32_e32 v76, 1.0, v76
	v_add_f32_e32 v70, 1.0, v70
	v_add_f32_e32 v78, 1.0, v78
	v_add_f32_e32 v64, 1.0, v64
	v_add_f32_e32 v72, 1.0, v72
	v_rcp_f32_e32 v66, v66
	v_rcp_f32_e32 v80, v80
	v_rcp_f32_e32 v68, v68
	v_rcp_f32_e32 v76, v76
	v_rcp_f32_e32 v70, v70
	v_rcp_f32_e32 v78, v78
	v_rcp_f32_e32 v64, v64
	v_rcp_f32_e32 v72, v72
	v_mul_f32_e32 v67, v67, v66
	v_mul_f32_e32 v80, v81, v80
	v_mul_f32_e32 v68, v69, v68
	v_mul_f32_e32 v69, v77, v76
	v_mul_f32_e32 v70, v71, v70
	v_mul_f32_e32 v71, v79, v78
	v_mul_f32_e32 v76, v65, v64
	v_mul_f32_e32 v72, v73, v72
	v_cvt_pk_bf16_f32 v64, v80, v68
	v_cvt_pk_bf16_f32 v65, v69, v70
	v_cvt_pk_bf16_f32 v66, v71, v76
	v_cvt_pk_bf16_f32 v67, v72, v67
	global_store_dwordx4 v[74:75], v[64:67], off
	s_nop 1
	v_mov_b32_e32 v66, v189
	s_nop 0
	v_mov_b32_e32 v64, v60
	v_mov_b32_e32 v60, v62
	v_mov_b32_e32 v62, v56
	v_mov_b32_e32 v56, v58
	v_mov_b32_e32 v65, v52
	v_mov_b32_e32 v52, v61
	v_mov_b32_e32 v61, v54
	v_mov_b32_e32 v54, v63
	v_mov_b32_e32 v63, v48
	v_mov_b32_e32 v48, v57
	v_mov_b32_e32 v57, v50
	v_mov_b32_e32 v50, v59
	s_nop 0
	v_fmamk_f32 v58, v66, 0x3a000000, v163
	v_mul_f32_e32 v59, 0x4f800000, v58
	v_cmp_gt_f32_e32 vcc, s48, v58
	s_nop 1
	v_cndmask_b32_e32 v66, v58, v59, vcc
	v_sqrt_f32_e32 v67, v66
	v_add_u32_e32 v58, 0x80, v136
	v_mad_i64_i32 v[58:59], s[8:9], v58, s49, v[122:123]
	v_add_u32_e32 v68, -1, v67
	v_add_u32_e32 v69, 1, v67
	v_fma_f32 v70, -v68, v67, v66
	v_fma_f32 v71, -v69, v67, v66
	v_cmp_ge_f32_e64 s[8:9], 0, v70
	v_lshl_add_u64 v[58:59], v[58:59], 0, v[120:121]
	s_nop 0
	v_cndmask_b32_e64 v67, v67, v68, s[8:9]
	v_cmp_lt_f32_e64 s[8:9], 0, v71
	s_nop 1
	v_cndmask_b32_e64 v67, v67, v69, s[8:9]
	v_mul_f32_e32 v68, 0x37800000, v67
	v_cndmask_b32_e32 v67, v67, v68, vcc
	v_cmp_class_f32_e32 vcc, v66, v164
	s_nop 1
	v_cndmask_b32_e32 v66, v67, v66, vcc
	v_div_scale_f32 v67, s[8:9], v66, v66, 1.0
	v_rcp_f32_e32 v68, v67
	v_div_scale_f32 v69, vcc, 1.0, v66, 1.0
	v_fma_f32 v70, -v67, v68, 1.0
	v_fmac_f32_e32 v68, v70, v68
	v_mul_f32_e32 v70, v69, v68
	v_fma_f32 v71, -v67, v70, v69
	v_fmac_f32_e32 v70, v71, v68
	v_fma_f32 v67, -v67, v70, v69
	v_div_fmas_f32 v67, v67, v68, v70
	v_div_fixup_f32 v66, v67, v66, 1.0
	v_pk_mul_f32 v[50:51], v[50:51], v[66:67] op_sel_hi:[1,0]
	v_pk_mul_f32 v[64:65], v[64:65], v[66:67] op_sel_hi:[1,0]
; __device__ __forceinline__ unsigned cvt_pk_bf16(float lo, float hi) { unsigned r; asm volatile("v_cvt_pk_bf16_f32 %0, %1, %2" : "=v"(r) : "v"(lo), "v"(hi)); return r; }
; __device__ __forceinline__ float exp2_fast(float x) { return __builtin_amdgcn_exp2f(x); }
; __device__ __forceinline__ float rstd_of(float sq, float inv_n) { return 1.0f / sqrtf(sq * inv_n + EPSN); }
;     __device__ __forceinline__ void operator()(const f32x4 (&acc)[2][2][4][2], const Unit& u, int wr, int wc, int fr, int fq) const {
;     ...
;             for (int m = 0; m < 4; ++m) {
;                 const int row = row0 + ai * HALF + m * 16;
;                 const float rs = PRENORM ? 1.0f : rstd_of(rowsq[row], 1.f / 2048.f);
;                 float hv[8];
; #pragma unroll
;                 for (int n = 0; n < 2; ++n)
; #pragma unroll
;                     for (int e = 0; e < 4; ++e) { const float g = acc[ai][0][m][n][e] * rs, uu = acc[ai][1][m][n][e] * rs;
;                         hv[n * 4 + e] = g * uu * __builtin_amdgcn_rcpf(1.0f + exp2_fast(-g * LOG2E)); }
;                 u32x4 w; w.x = cvt_pk_bf16(hv[0], hv[1]); w.y = cvt_pk_bf16(hv[2], hv[3]); w.z = cvt_pk_bf16(hv[4], hv[5]); w.w = cvt_pk_bf16(hv[6], hv[7]);
;                 *(u32x4*)(H + (size_t)row * DFF + col0) = w;
	v_pk_mul_f32 v[52:53], v[52:53], v[66:67] op_sel_hi:[1,0]
	v_pk_mul_f32 v[60:61], v[60:61], v[66:67] op_sel_hi:[1,0]
	v_pk_mul_f32 v[54:55], v[54:55], v[66:67] op_sel_hi:[1,0]
	v_pk_mul_f32 v[62:63], v[62:63], v[66:67] op_sel_hi:[1,0]
	v_pk_mul_f32 v[48:49], v[48:49], v[66:67] op_sel_hi:[1,0]
	v_pk_mul_f32 v[56:57], v[56:57], v[66:67] op_sel_hi:[1,0]
	v_mul_f32_e32 v51, v50, v51
	v_mul_f32_e32 v50, 0xbfb8aa3b, v50
	v_mul_f32_e32 v65, v64, v65
	v_mul_f32_e32 v64, 0xbfb8aa3b, v64
	v_mul_f32_e32 v53, v52, v53
	v_mul_f32_e32 v52, 0xbfb8aa3b, v52
	v_mul_f32_e32 v61, v60, v61
	v_mul_f32_e32 v60, 0xbfb8aa3b, v60
	v_mul_f32_e32 v55, v54, v55
	v_mul_f32_e32 v54, 0xbfb8aa3b, v54
	v_mul_f32_e32 v63, v62, v63
	v_mul_f32_e32 v62, 0xbfb8aa3b, v62
	v_mul_f32_e32 v49, v48, v49
	v_mul_f32_e32 v48, 0xbfb8aa3b, v48
	v_mul_f32_e32 v57, v56, v57
	v_mul_f32_e32 v56, 0xbfb8aa3b, v56
	v_exp_f32_e32 v50, v50
	v_exp_f32_e32 v64, v64
	v_exp_f32_e32 v52, v52
	v_exp_f32_e32 v60, v60
	v_exp_f32_e32 v54, v54
	v_exp_f32_e32 v62, v62
	v_exp_f32_e32 v48, v48
	v_exp_f32_e32 v56, v56
	v_add_f32_e32 v50, 1.0, v50
	v_add_f32_e32 v64, 1.0, v64
	v_add_f32_e32 v52, 1.0, v52
	v_add_f32_e32 v60, 1.0, v60
	v_add_f32_e32 v54, 1.0, v54
	v_add_f32_e32 v62, 1.0, v62
	v_add_f32_e32 v48, 1.0, v48
	v_add_f32_e32 v56, 1.0, v56
	v_rcp_f32_e32 v50, v50
	v_rcp_f32_e32 v64, v64
	v_rcp_f32_e32 v52, v52
	v_rcp_f32_e32 v60, v60
	v_rcp_f32_e32 v54, v54
	v_rcp_f32_e32 v62, v62
	v_rcp_f32_e32 v48, v48
	v_rcp_f32_e32 v56, v56
	v_mul_f32_e32 v51, v51, v50
	v_mul_f32_e32 v64, v65, v64
	v_mul_f32_e32 v52, v53, v52
	v_mul_f32_e32 v53, v61, v60
	v_mul_f32_e32 v54, v55, v54
	v_mul_f32_e32 v55, v63, v62
	v_mul_f32_e32 v60, v49, v48
	v_mul_f32_e32 v56, v57, v56
	v_cvt_pk_bf16_f32 v48, v64, v52
	v_cvt_pk_bf16_f32 v49, v53, v54
	v_cvt_pk_bf16_f32 v50, v55, v60
	v_cvt_pk_bf16_f32 v51, v56, v51
	global_store_dwordx4 v[58:59], v[48:51], off
	s_nop 1
	v_mov_b32_e32 v50, v190
	s_nop 0
	v_mov_b32_e32 v48, v44
	v_mov_b32_e32 v44, v46
	v_mov_b32_e32 v46, v40
	v_mov_b32_e32 v40, v42
	v_mov_b32_e32 v49, v36
	v_mov_b32_e32 v36, v45
	v_mov_b32_e32 v45, v38
	v_mov_b32_e32 v38, v47
	v_mov_b32_e32 v47, v32
	v_mov_b32_e32 v32, v41
	v_mov_b32_e32 v41, v34
	v_mov_b32_e32 v34, v43
	s_nop 0
	v_fmamk_f32 v42, v50, 0x3a000000, v163
	v_mul_f32_e32 v43, 0x4f800000, v42
	v_cmp_gt_f32_e32 vcc, s48, v42
	s_nop 1
	v_cndmask_b32_e32 v50, v42, v43, vcc
	v_sqrt_f32_e32 v51, v50
	v_add_u32_e32 v42, 0x90, v136
	v_mad_i64_i32 v[42:43], s[8:9], v42, s49, v[122:123]
	v_add_u32_e32 v52, -1, v51
	v_add_u32_e32 v53, 1, v51
	v_fma_f32 v54, -v52, v51, v50
	v_fma_f32 v55, -v53, v51, v50
	v_cmp_ge_f32_e64 s[8:9], 0, v54
	v_lshl_add_u64 v[42:43], v[42:43], 0, v[120:121]
	s_nop 0
	v_cndmask_b32_e64 v51, v51, v52, s[8:9]
	v_cmp_lt_f32_e64 s[8:9], 0, v55
	s_nop 1
	v_cndmask_b32_e64 v51, v51, v53, s[8:9]
	v_mul_f32_e32 v52, 0x37800000, v51
	v_cndmask_b32_e32 v51, v51, v52, vcc
	v_cmp_class_f32_e32 vcc, v50, v164
	s_nop 1
	v_cndmask_b32_e32 v50, v51, v50, vcc
	v_div_scale_f32 v51, s[8:9], v50, v50, 1.0
	v_rcp_f32_e32 v52, v51
	v_div_scale_f32 v53, vcc, 1.0, v50, 1.0
	v_fma_f32 v54, -v51, v52, 1.0
	v_fmac_f32_e32 v52, v54, v52
	v_mul_f32_e32 v54, v53, v52
	v_fma_f32 v55, -v51, v54, v53
	v_fmac_f32_e32 v54, v55, v52
	v_fma_f32 v51, -v51, v54, v53
	v_div_fmas_f32 v51, v51, v52, v54
	v_div_fixup_f32 v50, v51, v50, 1.0
	v_pk_mul_f32 v[34:35], v[34:35], v[50:51] op_sel_hi:[1,0]
	v_pk_mul_f32 v[48:49], v[48:49], v[50:51] op_sel_hi:[1,0]
	v_pk_mul_f32 v[36:37], v[36:37], v[50:51] op_sel_hi:[1,0]
	v_pk_mul_f32 v[44:45], v[44:45], v[50:51] op_sel_hi:[1,0]
	v_pk_mul_f32 v[38:39], v[38:39], v[50:51] op_sel_hi:[1,0]
	v_pk_mul_f32 v[46:47], v[46:47], v[50:51] op_sel_hi:[1,0]
	v_pk_mul_f32 v[32:33], v[32:33], v[50:51] op_sel_hi:[1,0]
	v_pk_mul_f32 v[40:41], v[40:41], v[50:51] op_sel_hi:[1,0]
	v_mul_f32_e32 v35, v34, v35
	v_mul_f32_e32 v34, 0xbfb8aa3b, v34
	v_mul_f32_e32 v49, v48, v49
	v_mul_f32_e32 v48, 0xbfb8aa3b, v48
	v_mul_f32_e32 v37, v36, v37
	v_mul_f32_e32 v36, 0xbfb8aa3b, v36
	v_mul_f32_e32 v45, v44, v45
	v_mul_f32_e32 v44, 0xbfb8aa3b, v44
	v_mul_f32_e32 v39, v38, v39
	v_mul_f32_e32 v38, 0xbfb8aa3b, v38
	v_mul_f32_e32 v47, v46, v47
	v_mul_f32_e32 v46, 0xbfb8aa3b, v46
	v_mul_f32_e32 v33, v32, v33
	v_mul_f32_e32 v32, 0xbfb8aa3b, v32
	v_mul_f32_e32 v41, v40, v41
	v_mul_f32_e32 v40, 0xbfb8aa3b, v40
	v_exp_f32_e32 v34, v34
	v_exp_f32_e32 v48, v48
	v_exp_f32_e32 v36, v36
	v_exp_f32_e32 v44, v44
	v_exp_f32_e32 v38, v38
	v_exp_f32_e32 v46, v46
	v_exp_f32_e32 v32, v32
	v_exp_f32_e32 v40, v40
	v_add_f32_e32 v34, 1.0, v34
	v_add_f32_e32 v48, 1.0, v48
	v_add_f32_e32 v36, 1.0, v36
	v_add_f32_e32 v44, 1.0, v44
	v_add_f32_e32 v38, 1.0, v38
	v_add_f32_e32 v46, 1.0, v46
	v_add_f32_e32 v32, 1.0, v32
	v_add_f32_e32 v40, 1.0, v40
	v_rcp_f32_e32 v34, v34
	v_rcp_f32_e32 v48, v48
	v_rcp_f32_e32 v36, v36
	v_rcp_f32_e32 v44, v44
	v_rcp_f32_e32 v38, v38
	v_rcp_f32_e32 v46, v46
	v_rcp_f32_e32 v32, v32
	v_rcp_f32_e32 v40, v40
	v_mul_f32_e32 v35, v35, v34
	v_mul_f32_e32 v48, v49, v48
	v_mul_f32_e32 v36, v37, v36
	v_mul_f32_e32 v37, v45, v44
	v_mul_f32_e32 v38, v39, v38
	v_mul_f32_e32 v39, v47, v46
	v_mul_f32_e32 v44, v33, v32
	v_mul_f32_e32 v40, v41, v40
	v_cvt_pk_bf16_f32 v32, v48, v36
	v_cvt_pk_bf16_f32 v33, v37, v38
	v_cvt_pk_bf16_f32 v34, v39, v44
	v_cvt_pk_bf16_f32 v35, v40, v35
	global_store_dwordx4 v[42:43], v[32:35], off
	s_nop 1
	v_mov_b32_e32 v34, v191
	s_nop 0
	v_mov_b32_e32 v32, v28
	v_mov_b32_e32 v28, v30
	v_mov_b32_e32 v30, v24
	v_mov_b32_e32 v24, v26
	v_mov_b32_e32 v33, v20
	v_mov_b32_e32 v20, v29
	v_mov_b32_e32 v29, v22
	v_mov_b32_e32 v22, v31
	v_mov_b32_e32 v31, v16
; __device__ __forceinline__ unsigned cvt_pk_bf16(float lo, float hi) { unsigned r; asm volatile("v_cvt_pk_bf16_f32 %0, %1, %2" : "=v"(r) : "v"(lo), "v"(hi)); return r; }
; __device__ __forceinline__ float rstd_of(float sq, float inv_n) { return 1.0f / sqrtf(sq * inv_n + EPSN); }
; __device__ __forceinline__ float exp2_fast(float x) { return __builtin_amdgcn_exp2f(x); }
; #define PG8_BAR __builtin_amdgcn_s_barrier()
;     __device__ __forceinline__ void operator()(const f32x4 (&acc)[2][2][4][2], const Unit& u, int wr, int wc, int fr, int fq) const {
;     ...
;             for (int m = 0; m < 4; ++m) {
;                 const int row = row0 + ai * HALF + m * 16;
;                 const float rs = PRENORM ? 1.0f : rstd_of(rowsq[row], 1.f / 2048.f);
;                 float hv[8];
; #pragma unroll
;                 for (int n = 0; n < 2; ++n)
; #pragma unroll
;                     for (int e = 0; e < 4; ++e) { const float g = acc[ai][0][m][n][e] * rs, uu = acc[ai][1][m][n][e] * rs;
;                         hv[n * 4 + e] = g * uu * __builtin_amdgcn_rcpf(1.0f + exp2_fast(-g * LOG2E)); }
;                 u32x4 w; w.x = cvt_pk_bf16(hv[0], hv[1]); w.y = cvt_pk_bf16(hv[2], hv[3]); w.z = cvt_pk_bf16(hv[4], hv[5]); w.w = cvt_pk_bf16(hv[6], hv[7]);
;                 *(u32x4*)(H + (size_t)row * DFF + col0) = w;
; template <class Epi, class Sched, bool ALIGN_EPI = false, bool SP2 = false>
; __device__ __forceinline__ void gemm_phase(PG8_LAS unsigned char* lds, const Gemm g, const Sched& S, const Epi& E) {
;     ...
;         if constexpr (!Epi::AFTER_DRAIN) { E(acc, cur, wr, wc, fr, fq); S.done(cur); }
;         if (!has_next) break;
; #pragma unroll
;         for (int a = 0; a < 2; ++a)
; #pragma unroll
;             for (int b = 0; b < 2; ++b)
; #pragma unroll
;                 for (int m = 0; m < 4; ++m)
; #pragma unroll
;                     for (int n = 0; n < 2; ++n) acc[a][b][m][n] = (f32x4){0.f, 0.f, 0.f, 0.f};
;         cur = nxt; cA = nA; cB = nB; ++ui;
;         if constexpr (ALIGN_EPI) { if (wr == 1) PG8_BAR; }
	v_mov_b32_e32 v16, v25
	v_mov_b32_e32 v25, v18
	v_mov_b32_e32 v18, v27
	s_nop 0
	v_fmamk_f32 v26, v34, 0x3a000000, v163
	v_mul_f32_e32 v27, 0x4f800000, v26
	v_cmp_gt_f32_e32 vcc, s48, v26
	s_nop 1
	v_cndmask_b32_e32 v34, v26, v27, vcc
	v_sqrt_f32_e32 v35, v34
	v_add_u32_e32 v26, 0xa0, v136
	v_mad_i64_i32 v[26:27], s[8:9], v26, s49, v[122:123]
	v_add_u32_e32 v36, -1, v35
	v_add_u32_e32 v37, 1, v35
	v_fma_f32 v38, -v36, v35, v34
	v_fma_f32 v39, -v37, v35, v34
	v_cmp_ge_f32_e64 s[8:9], 0, v38
	v_lshl_add_u64 v[26:27], v[26:27], 0, v[120:121]
	s_nop 0
	v_cndmask_b32_e64 v35, v35, v36, s[8:9]
	v_cmp_lt_f32_e64 s[8:9], 0, v39
	s_nop 1
	v_cndmask_b32_e64 v35, v35, v37, s[8:9]
	v_mul_f32_e32 v36, 0x37800000, v35
	v_cndmask_b32_e32 v35, v35, v36, vcc
	v_cmp_class_f32_e32 vcc, v34, v164
	s_nop 1
	v_cndmask_b32_e32 v34, v35, v34, vcc
	v_div_scale_f32 v35, s[8:9], v34, v34, 1.0
	v_rcp_f32_e32 v36, v35
	v_div_scale_f32 v37, vcc, 1.0, v34, 1.0
	v_fma_f32 v38, -v35, v36, 1.0
	v_fmac_f32_e32 v36, v38, v36
	v_mul_f32_e32 v38, v37, v36
	v_fma_f32 v39, -v35, v38, v37
	v_fmac_f32_e32 v38, v39, v36
	v_fma_f32 v35, -v35, v38, v37
	v_div_fmas_f32 v35, v35, v36, v38
	v_div_fixup_f32 v34, v35, v34, 1.0
	v_pk_mul_f32 v[18:19], v[18:19], v[34:35] op_sel_hi:[1,0]
	v_pk_mul_f32 v[32:33], v[32:33], v[34:35] op_sel_hi:[1,0]
	v_pk_mul_f32 v[20:21], v[20:21], v[34:35] op_sel_hi:[1,0]
	v_pk_mul_f32 v[28:29], v[28:29], v[34:35] op_sel_hi:[1,0]
	v_pk_mul_f32 v[22:23], v[22:23], v[34:35] op_sel_hi:[1,0]
	v_pk_mul_f32 v[30:31], v[30:31], v[34:35] op_sel_hi:[1,0]
	v_pk_mul_f32 v[16:17], v[16:17], v[34:35] op_sel_hi:[1,0]
	v_pk_mul_f32 v[24:25], v[24:25], v[34:35] op_sel_hi:[1,0]
	v_mul_f32_e32 v19, v18, v19
	v_mul_f32_e32 v18, 0xbfb8aa3b, v18
	v_mul_f32_e32 v33, v32, v33
	v_mul_f32_e32 v32, 0xbfb8aa3b, v32
	v_mul_f32_e32 v21, v20, v21
	v_mul_f32_e32 v20, 0xbfb8aa3b, v20
	v_mul_f32_e32 v29, v28, v29
	v_mul_f32_e32 v28, 0xbfb8aa3b, v28
	v_mul_f32_e32 v23, v22, v23
	v_mul_f32_e32 v22, 0xbfb8aa3b, v22
	v_mul_f32_e32 v31, v30, v31
	v_mul_f32_e32 v30, 0xbfb8aa3b, v30
	v_mul_f32_e32 v17, v16, v17
	v_mul_f32_e32 v16, 0xbfb8aa3b, v16
	v_mul_f32_e32 v25, v24, v25
	v_mul_f32_e32 v24, 0xbfb8aa3b, v24
	v_exp_f32_e32 v18, v18
	v_exp_f32_e32 v32, v32
	v_exp_f32_e32 v20, v20
	v_exp_f32_e32 v28, v28
	v_exp_f32_e32 v22, v22
	v_exp_f32_e32 v30, v30
	v_exp_f32_e32 v16, v16
	v_exp_f32_e32 v24, v24
	v_add_f32_e32 v18, 1.0, v18
	v_add_f32_e32 v32, 1.0, v32
	v_add_f32_e32 v20, 1.0, v20
	v_add_f32_e32 v28, 1.0, v28
	v_add_f32_e32 v22, 1.0, v22
	v_add_f32_e32 v30, 1.0, v30
	v_add_f32_e32 v16, 1.0, v16
	v_add_f32_e32 v24, 1.0, v24
	v_rcp_f32_e32 v18, v18
	v_rcp_f32_e32 v32, v32
	v_rcp_f32_e32 v20, v20
	v_rcp_f32_e32 v28, v28
	v_rcp_f32_e32 v22, v22
	v_rcp_f32_e32 v30, v30
	v_rcp_f32_e32 v16, v16
	v_rcp_f32_e32 v24, v24
	v_mul_f32_e32 v19, v19, v18
	v_mul_f32_e32 v32, v33, v32
	v_mul_f32_e32 v20, v21, v20
	v_mul_f32_e32 v21, v29, v28
	v_mul_f32_e32 v22, v23, v22
	v_mul_f32_e32 v23, v31, v30
	v_mul_f32_e32 v28, v17, v16
	v_mul_f32_e32 v24, v25, v24
	v_cvt_pk_bf16_f32 v16, v32, v20
	v_cvt_pk_bf16_f32 v17, v21, v22
	v_cvt_pk_bf16_f32 v18, v23, v28
	v_cvt_pk_bf16_f32 v19, v24, v19
	global_store_dwordx4 v[26:27], v[16:19], off
	s_nop 1
	v_mov_b32_e32 v18, v192
	s_nop 0
	v_mov_b32_e32 v17, v4
	v_mov_b32_e32 v4, v13
	v_mov_b32_e32 v13, v6
	v_mov_b32_e32 v6, v15
	v_mov_b32_e32 v15, v0
	v_mov_b32_e32 v0, v9
	v_mov_b32_e32 v9, v2
	v_mov_b32_e32 v2, v11
	v_mov_b32_e32 v16, v12
	v_mov_b32_e32 v12, v14
	v_mov_b32_e32 v14, v8
	v_mov_b32_e32 v8, v10
	v_add_u32_e32 v10, 0xb0, v136
	s_nop 0
	v_fmamk_f32 v11, v18, 0x3a000000, v163
	v_mul_f32_e32 v18, 0x4f800000, v11
	v_cmp_gt_f32_e32 vcc, s48, v11
	s_nop 1
	v_cndmask_b32_e32 v18, v11, v18, vcc
	v_sqrt_f32_e32 v19, v18
	v_mad_i64_i32 v[10:11], s[8:9], v10, s49, v[122:123]
	v_lshl_add_u64 v[10:11], v[10:11], 0, v[120:121]
	v_add_u32_e32 v20, -1, v19
	v_add_u32_e32 v21, 1, v19
	v_fma_f32 v22, -v20, v19, v18
	v_fma_f32 v23, -v21, v19, v18
	v_cmp_ge_f32_e64 s[8:9], 0, v22
	s_nop 1
	v_cndmask_b32_e64 v19, v19, v20, s[8:9]
	v_cmp_lt_f32_e64 s[8:9], 0, v23
	s_nop 1
	v_cndmask_b32_e64 v19, v19, v21, s[8:9]
	v_mul_f32_e32 v20, 0x37800000, v19
	v_cndmask_b32_e32 v19, v19, v20, vcc
	v_cmp_class_f32_e32 vcc, v18, v164
	s_nop 1
	v_cndmask_b32_e32 v18, v19, v18, vcc
	v_div_scale_f32 v19, s[8:9], v18, v18, 1.0
	v_rcp_f32_e32 v20, v19
	v_div_scale_f32 v21, vcc, 1.0, v18, 1.0
	v_fma_f32 v22, -v19, v20, 1.0
	v_fmac_f32_e32 v20, v22, v20
	v_mul_f32_e32 v22, v21, v20
	v_fma_f32 v23, -v19, v22, v21
	v_fmac_f32_e32 v22, v23, v20
	v_fma_f32 v19, -v19, v22, v21
	v_div_fmas_f32 v19, v19, v20, v22
	v_div_fixup_f32 v18, v19, v18, 1.0
	v_pk_mul_f32 v[2:3], v[2:3], v[18:19] op_sel_hi:[1,0]
	v_pk_mul_f32 v[16:17], v[16:17], v[18:19] op_sel_hi:[1,0]
	v_pk_mul_f32 v[4:5], v[4:5], v[18:19] op_sel_hi:[1,0]
	v_pk_mul_f32 v[12:13], v[12:13], v[18:19] op_sel_hi:[1,0]
	v_pk_mul_f32 v[6:7], v[6:7], v[18:19] op_sel_hi:[1,0]
	v_pk_mul_f32 v[14:15], v[14:15], v[18:19] op_sel_hi:[1,0]
	v_pk_mul_f32 v[0:1], v[0:1], v[18:19] op_sel_hi:[1,0]
	v_pk_mul_f32 v[8:9], v[8:9], v[18:19] op_sel_hi:[1,0]
	v_mul_f32_e32 v3, v2, v3
	v_mul_f32_e32 v2, 0xbfb8aa3b, v2
	v_mul_f32_e32 v17, v16, v17
	v_mul_f32_e32 v16, 0xbfb8aa3b, v16
	v_mul_f32_e32 v5, v4, v5
	v_mul_f32_e32 v4, 0xbfb8aa3b, v4
	v_mul_f32_e32 v13, v12, v13
	v_mul_f32_e32 v12, 0xbfb8aa3b, v12
	v_mul_f32_e32 v7, v6, v7
	v_mul_f32_e32 v6, 0xbfb8aa3b, v6
	v_mul_f32_e32 v15, v14, v15
	v_mul_f32_e32 v14, 0xbfb8aa3b, v14
	v_mul_f32_e32 v1, v0, v1
	v_mul_f32_e32 v0, 0xbfb8aa3b, v0
	v_mul_f32_e32 v9, v8, v9
	v_mul_f32_e32 v8, 0xbfb8aa3b, v8
	v_exp_f32_e32 v2, v2
	v_exp_f32_e32 v16, v16
	v_exp_f32_e32 v4, v4
	v_exp_f32_e32 v12, v12
	v_exp_f32_e32 v6, v6
	v_exp_f32_e32 v14, v14
	v_exp_f32_e32 v0, v0
	v_exp_f32_e32 v8, v8
	v_add_f32_e32 v2, 1.0, v2
	v_add_f32_e32 v16, 1.0, v16
	v_add_f32_e32 v4, 1.0, v4
	v_add_f32_e32 v12, 1.0, v12
	v_add_f32_e32 v6, 1.0, v6
	v_add_f32_e32 v14, 1.0, v14
	v_add_f32_e32 v0, 1.0, v0
	v_add_f32_e32 v8, 1.0, v8
	v_rcp_f32_e32 v2, v2
	v_rcp_f32_e32 v16, v16
	v_rcp_f32_e32 v4, v4
	v_rcp_f32_e32 v12, v12
	v_rcp_f32_e32 v6, v6
	v_rcp_f32_e32 v14, v14
	v_rcp_f32_e32 v0, v0
	v_rcp_f32_e32 v8, v8
	s_andn2_b64 vcc, exec, s[6:7]
	v_mul_f32_e32 v3, v3, v2
	s_mov_b64 s[6:7], -1
	v_mul_f32_e32 v16, v17, v16
	v_mul_f32_e32 v4, v5, v4
	v_mul_f32_e32 v5, v13, v12
	v_mul_f32_e32 v6, v7, v6
	v_mul_f32_e32 v7, v15, v14
	v_mul_f32_e32 v12, v1, v0
	v_mul_f32_e32 v8, v9, v8
	v_cvt_pk_bf16_f32 v0, v16, v4
	v_cvt_pk_bf16_f32 v1, v5, v6
	v_cvt_pk_bf16_f32 v2, v7, v12
	v_cvt_pk_bf16_f32 v3, v8, v3
	global_store_dwordx4 v[10:11], v[0:3], off
	s_cbranch_vccnz .LBB0_1271
	s_andn2_b64 vcc, exec, s[4:5]
	s_cbranch_vccnz .LBB0_1270
	s_barrier
	s_branch .LBB0_1270
